# plus P7: cross-half top-3 merge by permlane32 swap + insertion network, and the 64-counter inclusive prefix by a DPP row_shr/row_bcast scan instead of six ds_bpermute steps
# speedup vs baseline: 1.0017x; 1.0007x over previous
.LBB0_860:
	s_nop 10
	v_ashrrev_i32_e32 v83, 31, v2
	v_or_b32_e32 v83, 0x80000000, v83
	v_bitop3_b32 v2, v83, s57, v2 bitop3:0x48
	v_ashrrev_i32_e32 v83, 31, v3
	v_ashrrev_i32_e32 v85, 31, v18
	v_or_b32_e32 v83, 0x80000000, v83
	v_or_b32_e32 v85, 0x80000000, v85
	v_bitop3_b32 v3, v83, s57, v3 bitop3:0x48
	v_ashrrev_i32_e32 v83, 31, v4
	v_bitop3_b32 v18, v85, s57, v18 bitop3:0x48
	v_ashrrev_i32_e32 v85, 31, v19
	v_or_b32_e32 v83, 0x80000000, v83
	v_or_b32_e32 v85, 0x80000000, v85
	v_bitop3_b32 v4, v83, s57, v4 bitop3:0x48
	v_ashrrev_i32_e32 v83, 31, v5
	s_sub_i32 s18, s59, 32
	v_bitop3_b32 v18, v18, 63, v92 bitop3:0x36
	v_cmp_gt_u32_e32 vcc, s59, v92
	v_bitop3_b32 v19, v85, s57, v19 bitop3:0x48
	v_ashrrev_i32_e32 v85, 31, v20
	v_or_b32_e32 v83, 0x80000000, v83
	v_cndmask_b32_e32 v18, 0, v18, vcc
	v_bitop3_b32 v2, v2, 31, v92 bitop3:0x36
	v_cmp_gt_i32_e32 vcc, s18, v92
	v_or_b32_e32 v85, 0x80000000, v85
	v_bitop3_b32 v5, v83, s57, v5 bitop3:0x48
	v_ashrrev_i32_e32 v83, 31, v6
	v_cndmask_b32_e32 v2, 0, v2, vcc
	v_bitop3_b32 v19, v19, 62, v92 bitop3:0x36
	v_cmp_gt_u32_e32 vcc, s59, v106
	v_bitop3_b32 v20, v85, s57, v20 bitop3:0x48
	v_ashrrev_i32_e32 v85, 31, v21
	v_or_b32_e32 v83, 0x80000000, v83
	v_cndmask_b32_e32 v19, 0, v19, vcc
	v_bitop3_b32 v3, v3, 30, v92 bitop3:0x36
	v_cmp_gt_i32_e32 vcc, s18, v106
	v_or_b32_e32 v85, 0x80000000, v85
	v_bitop3_b32 v6, v83, s57, v6 bitop3:0x48
	v_ashrrev_i32_e32 v83, 31, v7
	v_cndmask_b32_e32 v3, 0, v3, vcc
	v_bitop3_b32 v20, v20, 61, v92 bitop3:0x36
	v_cmp_gt_u32_e32 vcc, s59, v95
	v_bitop3_b32 v21, v85, s57, v21 bitop3:0x48
	v_ashrrev_i32_e32 v85, 31, v22
	v_or_b32_e32 v83, 0x80000000, v83
	v_cndmask_b32_e32 v20, 0, v20, vcc
	v_bitop3_b32 v4, v4, 29, v92 bitop3:0x36
	v_cmp_gt_i32_e32 vcc, s18, v95
	v_or_b32_e32 v85, 0x80000000, v85
	v_bitop3_b32 v7, v83, s57, v7 bitop3:0x48
	v_ashrrev_i32_e32 v83, 31, v8
	v_cndmask_b32_e32 v4, 0, v4, vcc
	v_bitop3_b32 v21, v21, 60, v92 bitop3:0x36
	v_cmp_gt_u32_e32 vcc, s59, v107
	v_bitop3_b32 v22, v85, s57, v22 bitop3:0x48
	v_ashrrev_i32_e32 v85, 31, v23
	v_or_b32_e32 v83, 0x80000000, v83
	v_cndmask_b32_e32 v21, 0, v21, vcc
	v_bitop3_b32 v5, v5, 28, v92 bitop3:0x36
	v_cmp_gt_i32_e32 vcc, s18, v107
	v_sub_u32_e32 v22, v22, v92
	v_or_b32_e32 v85, 0x80000000, v85
	v_bitop3_b32 v8, v83, s57, v8 bitop3:0x48
	v_ashrrev_i32_e32 v83, 31, v9
	v_cndmask_b32_e32 v5, 0, v5, vcc
	v_add_u32_e32 v22, 55, v22
	v_cmp_gt_u32_e32 vcc, s59, v96
	v_sub_u32_e32 v6, v6, v92
	v_bitop3_b32 v23, v85, s57, v23 bitop3:0x48
	v_ashrrev_i32_e32 v85, 31, v24
	v_or_b32_e32 v83, 0x80000000, v83
	v_cndmask_b32_e32 v22, 0, v22, vcc
	v_add_u32_e32 v6, 23, v6
	v_cmp_gt_i32_e32 vcc, s18, v96
	v_sub_u32_e32 v23, v23, v92
	v_or_b32_e32 v85, 0x80000000, v85
	v_bitop3_b32 v9, v83, s57, v9 bitop3:0x48
	v_ashrrev_i32_e32 v83, 31, v10
	v_cndmask_b32_e32 v6, 0, v6, vcc
	v_add_u32_e32 v23, 54, v23
	v_cmp_gt_u32_e32 vcc, s59, v108
	v_sub_u32_e32 v7, v7, v92
	v_bitop3_b32 v24, v85, s57, v24 bitop3:0x48
	v_ashrrev_i32_e32 v85, 31, v25
	v_or_b32_e32 v83, 0x80000000, v83
	v_cndmask_b32_e32 v23, 0, v23, vcc
	v_add_u32_e32 v7, 22, v7
	v_cmp_gt_i32_e32 vcc, s18, v108
	v_sub_u32_e32 v24, v24, v92
	v_or_b32_e32 v85, 0x80000000, v85
	v_bitop3_b32 v10, v83, s57, v10 bitop3:0x48
	v_ashrrev_i32_e32 v83, 31, v11
	v_cndmask_b32_e32 v7, 0, v7, vcc
	v_add_u32_e32 v24, 53, v24
	v_cmp_gt_u32_e32 vcc, s59, v97
	v_sub_u32_e32 v8, v8, v92
	v_bitop3_b32 v25, v85, s57, v25 bitop3:0x48
	v_ashrrev_i32_e32 v85, 31, v26
	v_or_b32_e32 v83, 0x80000000, v83
	v_cndmask_b32_e32 v24, 0, v24, vcc
	v_add_u32_e32 v8, 21, v8
	v_cmp_gt_i32_e32 vcc, s18, v97
	v_sub_u32_e32 v25, v25, v92
	v_or_b32_e32 v85, 0x80000000, v85
	v_bitop3_b32 v11, v83, s57, v11 bitop3:0x48
	v_ashrrev_i32_e32 v83, 31, v12
	v_cndmask_b32_e32 v8, 0, v8, vcc
	v_add_u32_e32 v25, 52, v25
	v_cmp_gt_u32_e32 vcc, s59, v109
	v_sub_u32_e32 v9, v9, v92
	v_bitop3_b32 v26, v85, s57, v26 bitop3:0x48
	v_ashrrev_i32_e32 v85, 31, v27
	v_or_b32_e32 v83, 0x80000000, v83
	v_cndmask_b32_e32 v25, 0, v25, vcc
	v_add_u32_e32 v9, 20, v9
	v_cmp_gt_i32_e32 vcc, s18, v109
	v_sub_u32_e32 v26, v26, v92
	v_or_b32_e32 v85, 0x80000000, v85
	v_bitop3_b32 v12, v83, s57, v12 bitop3:0x48
	v_ashrrev_i32_e32 v83, 31, v13
	v_cndmask_b32_e32 v9, 0, v9, vcc
	v_add_u32_e32 v26, 47, v26
	v_cmp_gt_u32_e32 vcc, s59, v98
	v_bitop3_b32 v27, v85, s57, v27 bitop3:0x48
	v_ashrrev_i32_e32 v85, 31, v28
	v_or_b32_e32 v83, 0x80000000, v83
	v_cndmask_b32_e32 v26, 0, v26, vcc
	v_bitop3_b32 v10, v10, 15, v92 bitop3:0x36
	v_cmp_gt_i32_e32 vcc, s18, v98
	v_sub_u32_e32 v27, v27, v92
	v_or_b32_e32 v85, 0x80000000, v85
	v_bitop3_b32 v13, v83, s57, v13 bitop3:0x48
	v_ashrrev_i32_e32 v83, 31, v14
	v_cndmask_b32_e32 v10, 0, v10, vcc
	v_add_u32_e32 v27, 46, v27
	v_cmp_gt_u32_e32 vcc, s59, v110
	v_sub_u32_e32 v11, v11, v92
	v_bitop3_b32 v28, v85, s57, v28 bitop3:0x48
	v_ashrrev_i32_e32 v85, 31, v29
	v_or_b32_e32 v83, 0x80000000, v83
	v_cndmask_b32_e32 v27, 0, v27, vcc
	v_add_u32_e32 v11, 14, v11
	v_cmp_gt_i32_e32 vcc, s18, v110
	v_sub_u32_e32 v28, v28, v92
	v_or_b32_e32 v85, 0x80000000, v85
	v_bitop3_b32 v14, v83, s57, v14 bitop3:0x48
	v_ashrrev_i32_e32 v83, 31, v15
	v_cndmask_b32_e32 v11, 0, v11, vcc
	v_add_u32_e32 v28, 45, v28
	v_cmp_gt_u32_e32 vcc, s59, v99
	v_sub_u32_e32 v12, v12, v92
	v_bitop3_b32 v29, v85, s57, v29 bitop3:0x48
	v_ashrrev_i32_e32 v85, 31, v30
	v_or_b32_e32 v83, 0x80000000, v83
	v_cndmask_b32_e32 v28, 0, v28, vcc
	v_add_u32_e32 v12, 13, v12
	v_cmp_gt_i32_e32 vcc, s18, v99
	v_sub_u32_e32 v29, v29, v92
	v_or_b32_e32 v85, 0x80000000, v85
	v_bitop3_b32 v15, v83, s57, v15 bitop3:0x48
	v_ashrrev_i32_e32 v83, 31, v16
	v_cndmask_b32_e32 v12, 0, v12, vcc
	v_add_u32_e32 v29, 44, v29
	v_cmp_gt_u32_e32 vcc, s59, v111
	v_sub_u32_e32 v13, v13, v92
	v_bitop3_b32 v30, v85, s57, v30 bitop3:0x48
	v_ashrrev_i32_e32 v85, 31, v31
	v_or_b32_e32 v83, 0x80000000, v83
	v_cndmask_b32_e32 v29, 0, v29, vcc
	v_add_u32_e32 v13, 12, v13
	v_cmp_gt_i32_e32 vcc, s18, v111
	v_sub_u32_e32 v30, v30, v92
	v_or_b32_e32 v85, 0x80000000, v85
	v_bitop3_b32 v16, v83, s57, v16 bitop3:0x48
	v_ashrrev_i32_e32 v83, 31, v17
	v_cndmask_b32_e32 v13, 0, v13, vcc
	v_add_u32_e32 v30, 39, v30
	v_cmp_gt_u32_e32 vcc, s59, v100
	v_bitop3_b32 v31, v85, s57, v31 bitop3:0x48
	v_ashrrev_i32_e32 v85, 31, v32
	v_or_b32_e32 v83, 0x80000000, v83
	v_cndmask_b32_e32 v30, 0, v30, vcc
	v_bitop3_b32 v14, v14, 7, v92 bitop3:0x36
	v_cmp_gt_i32_e32 vcc, s18, v100
	v_sub_u32_e32 v31, v31, v92
	v_or_b32_e32 v85, 0x80000000, v85
	v_bitop3_b32 v17, v83, s57, v17 bitop3:0x48
	s_nop 0
	v_cndmask_b32_e32 v14, 0, v14, vcc
	v_add_u32_e32 v31, 38, v31
	v_cmp_gt_u32_e32 vcc, s59, v112
	v_sub_u32_e32 v15, v15, v92
	v_bitop3_b32 v32, v85, s57, v32 bitop3:0x48
	v_ashrrev_i32_e32 v85, 31, v33
	s_nop 0
	v_cndmask_b32_e32 v31, 0, v31, vcc
	v_add_u32_e32 v15, 6, v15
	v_cmp_gt_i32_e32 vcc, s18, v112
	v_sub_u32_e32 v32, v32, v92
	v_or_b32_e32 v85, 0x80000000, v85
	s_nop 0
	v_cndmask_b32_e32 v15, 0, v15, vcc
	v_add_u32_e32 v32, 37, v32
	v_cmp_gt_u32_e32 vcc, s59, v101
	v_sub_u32_e32 v16, v16, v92
	v_bitop3_b32 v33, v85, s57, v33 bitop3:0x48
	s_nop 0
	v_cndmask_b32_e32 v32, 0, v32, vcc
	v_add_u32_e32 v16, 5, v16
	v_cmp_gt_i32_e32 vcc, s18, v101
	v_sub_u32_e32 v33, v33, v92
	s_nop 0
	v_cndmask_b32_e32 v16, 0, v16, vcc
	v_add_u32_e32 v33, 36, v33
	v_cmp_gt_u32_e32 vcc, s59, v113
	s_nop 0
	s_nop 0
	v_cndmask_b32_e32 v33, 0, v33, vcc
	s_nop 0
	s_nop 0
	s_nop 0
	s_nop 0
	s_nop 0
	v_sub_u32_e32 v17, v17, v92
	s_nop 0
	v_add_u32_e32 v17, 4, v17
	v_cmp_gt_i32_e32 vcc, s18, v113
	s_nop 0
	s_nop 0
	v_cndmask_b32_e32 v17, 0, v17, vcc
	s_nop 0
	s_nop 1
	v_max_u32_e32 v85, v18, v19
	v_min_u32_e32 v86, v18, v19
	v_mov_b32_e32 v127, 0
	v_med3_u32 v127, v86, v127, v20
	v_med3_u32 v86, v85, v86, v20
	v_max_u32_e32 v85, v85, v20
	v_med3_u32 v127, v86, v127, v21
	v_med3_u32 v86, v85, v86, v21
	v_max_u32_e32 v85, v85, v21
	v_med3_u32 v127, v86, v127, v22
	v_med3_u32 v86, v85, v86, v22
	v_max_u32_e32 v85, v85, v22
	v_med3_u32 v127, v86, v127, v23
	v_med3_u32 v86, v85, v86, v23
	v_max_u32_e32 v85, v85, v23
	v_med3_u32 v127, v86, v127, v24
	v_med3_u32 v86, v85, v86, v24
	v_max_u32_e32 v85, v85, v24
	v_med3_u32 v127, v86, v127, v25
	v_med3_u32 v86, v85, v86, v25
	v_max_u32_e32 v85, v85, v25
	v_med3_u32 v127, v86, v127, v26
	v_med3_u32 v86, v85, v86, v26
	v_max_u32_e32 v85, v85, v26
	v_med3_u32 v127, v86, v127, v27
	v_med3_u32 v86, v85, v86, v27
	v_max_u32_e32 v85, v85, v27
	v_med3_u32 v127, v86, v127, v28
	v_med3_u32 v86, v85, v86, v28
	v_max_u32_e32 v85, v85, v28
	v_med3_u32 v127, v86, v127, v29
	v_med3_u32 v86, v85, v86, v29
	v_max_u32_e32 v85, v85, v29
	v_med3_u32 v127, v86, v127, v30
	v_med3_u32 v86, v85, v86, v30
	v_max_u32_e32 v85, v85, v30
	v_med3_u32 v127, v86, v127, v31
	v_med3_u32 v86, v85, v86, v31
	v_max_u32_e32 v85, v85, v31
	v_med3_u32 v127, v86, v127, v32
	v_med3_u32 v86, v85, v86, v32
	v_max_u32_e32 v85, v85, v32
	v_med3_u32 v127, v86, v127, v33
	v_med3_u32 v86, v85, v86, v33
	v_max_u32_e32 v85, v85, v33
	v_med3_u32 v127, v86, v127, v2
	v_med3_u32 v86, v85, v86, v2
	v_max_u32_e32 v85, v85, v2
	v_med3_u32 v127, v86, v127, v3
	v_med3_u32 v86, v85, v86, v3
	v_max_u32_e32 v85, v85, v3
	v_med3_u32 v127, v86, v127, v4
	v_med3_u32 v86, v85, v86, v4
	v_max_u32_e32 v85, v85, v4
	v_med3_u32 v127, v86, v127, v5
	v_med3_u32 v86, v85, v86, v5
	v_max_u32_e32 v85, v85, v5
	v_med3_u32 v127, v86, v127, v6
	v_med3_u32 v86, v85, v86, v6
	v_max_u32_e32 v85, v85, v6
	v_med3_u32 v127, v86, v127, v7
	v_med3_u32 v86, v85, v86, v7
	v_max_u32_e32 v85, v85, v7
	v_med3_u32 v127, v86, v127, v8
	v_med3_u32 v86, v85, v86, v8
	v_max_u32_e32 v85, v85, v8
	v_med3_u32 v127, v86, v127, v9
	v_med3_u32 v86, v85, v86, v9
	v_max_u32_e32 v85, v85, v9
	v_med3_u32 v127, v86, v127, v10
	v_med3_u32 v86, v85, v86, v10
	v_max_u32_e32 v85, v85, v10
	v_med3_u32 v127, v86, v127, v11
	v_med3_u32 v86, v85, v86, v11
	v_max_u32_e32 v85, v85, v11
	v_med3_u32 v127, v86, v127, v12
	v_med3_u32 v86, v85, v86, v12
	v_max_u32_e32 v85, v85, v12
	v_med3_u32 v127, v86, v127, v13
	v_med3_u32 v86, v85, v86, v13
	v_max_u32_e32 v85, v85, v13
	v_med3_u32 v127, v86, v127, v14
	v_med3_u32 v86, v85, v86, v14
	v_max_u32_e32 v85, v85, v14
	v_med3_u32 v127, v86, v127, v15
	v_med3_u32 v86, v85, v86, v15
	v_max_u32_e32 v85, v85, v15
	v_med3_u32 v127, v86, v127, v16
	v_med3_u32 v86, v85, v86, v16
	v_max_u32_e32 v85, v85, v16
	v_med3_u32 v127, v86, v127, v17
	v_med3_u32 v86, v85, v86, v17
	v_max_u32_e32 v85, v85, v17
	v_mov_b32_e32 v2, v127
	v_and_b32_e32 v8, 64, v126
	v_add_u32_e32 v4, 64, v8
	v_mov_b32_e32 v9, v85
	v_mov_b32_e32 v3, v85
	v_mov_b32_e32 v10, v86
	v_mov_b32_e32 v4, v86
	v_mov_b32_e32 v11, v2
	v_mov_b32_e32 v5, v2
	s_nop 1
	v_permlane32_swap_b32_e32 v9, v3
	v_permlane32_swap_b32_e32 v10, v4
	v_permlane32_swap_b32_e32 v11, v5
	v_med3_u32 v2, v86, v2, v3
	v_med3_u32 v86, v85, v86, v3
	v_max_u32_e32 v85, v85, v3
	v_med3_u32 v2, v86, v2, v4
	v_med3_u32 v86, v85, v86, v4
	v_max_u32_e32 v85, v85, v4
	v_med3_u32 v2, v86, v2, v5
	v_med3_u32 v86, v85, v86, v5
	v_max_u32_e32 v85, v85, v5
	v_bitop3_b32 v5, v85, 63, v85 bitop3:0xc
	v_bitop3_b32 v3, v86, 63, v86 bitop3:0xc
	v_bitop3_b32 v2, v2, 63, v2 bitop3:0xc
	v_mov_b32_e32 v7, 0
	v_mov_b32_e32 v6, 0
	v_mov_b32_e32 v4, 0
	s_and_saveexec_b64 s[18:19], s[0:1]
	s_cbranch_execz .LBB0_866
	s_cmp_eq_u32 s59, 0
	s_cbranch_scc1 .LBB0_881
	v_lshl_add_u32 v4, v5, 2, 0
	ds_add_rtn_u32 v7, v4, v125 offset:32768
	v_mov_b32_e32 v4, 0
	s_cmp_lt_u32 s59, 2
	v_mov_b32_e32 v6, 0
	s_cbranch_scc1 .LBB0_864

.LBB0_866:
	s_or_b64 exec, exec, s[18:19]
	s_andn2_b64 vcc, exec, s[24:25]
	s_waitcnt lgkmcnt(0)
	s_barrier
	s_cbranch_vccnz .LBB0_874
	ds_read_b32 v9, v114 offset:32768
	s_mul_i32 s18, s50, 0x90
	s_mul_hi_i32 s19, s50, 0x90
	s_add_u32 s18, s51, s18
	s_addc_u32 s19, s52, s19
	s_waitcnt lgkmcnt(0)
	v_mov_b32_e32 v8, v9
	s_nop 1
	v_add_u32_dpp v8, v8, v8 row_shr:1 row_mask:0xf bank_mask:0xf bound_ctrl:1
	s_nop 1
	v_add_u32_dpp v8, v8, v8 row_shr:2 row_mask:0xf bank_mask:0xf bound_ctrl:1
	s_nop 1
	v_add_u32_dpp v8, v8, v8 row_shr:4 row_mask:0xf bank_mask:0xf bound_ctrl:1
	s_nop 1
	v_add_u32_dpp v8, v8, v8 row_shr:8 row_mask:0xf bank_mask:0xf bound_ctrl:1
	s_nop 1
	v_add_u32_dpp v8, v8, v8 row_bcast:15 row_mask:0xa bank_mask:0xf
	s_nop 1
	v_add_u32_dpp v8, v8, v8 row_bcast:31 row_mask:0xc bank_mask:0xf
	v_lshlrev_b32_e32 v10, 1, v198
	ds_write_b32 v114, v8 offset:33284
	s_and_saveexec_b64 s[46:47], s[10:11]
	s_xor_b64 s[46:47], exec, s[46:47]
	s_cbranch_execz .LBB0_869
	global_store_short v10, v8, s[18:19] offset:2
